# sample-sequence conv group: its wave touches the sequence's 56 KB of conv state at the start of the conv phase (the row loop reads it one dependent round trip per row)
# speedup vs baseline: 1.0304x; 1.0025x over previous
.LBB0_498:
	v_mbcnt_lo_u32_b32 v0, -1, 0
	v_mbcnt_hi_u32_b32 v0, -1, v0
	s_mov_b64 s[14:15], s[96:97]
	v_add_u32_e32 v6, s73, v0
	s_load_dwordx4 s[16:19], s[14:15], 0xd8
	s_load_dwordx2 s[40:41], s[14:15], 0x20
	s_load_dwordx8 s[4:11], s[14:15], 0x78
	s_and_b32 s98, s92, 7
	s_or_b32 s98, s98, s93
	s_cmp_eq_u32 s98, 0
	s_cbranch_scc0 .Lsconv_pf_done
	s_waitcnt lgkmcnt(0)
	s_lshr_b32 s98, s92, 3
	s_mul_i32 s98, s98, 0xf000
	s_add_u32 s98, s40, s98
	s_addc_u32 s99, s41, 0
	v_lshlrev_b32_e32 v249, 7, v0
	global_load_dword v252, v249, s[98:99]
	s_add_u32 s98, s98, 0x2000
	s_addc_u32 s99, s99, 0
	global_load_dword v252, v249, s[98:99]
	s_add_u32 s98, s98, 0x2000
	s_addc_u32 s99, s99, 0
	global_load_dword v252, v249, s[98:99]
	s_add_u32 s98, s98, 0x2000
	s_addc_u32 s99, s99, 0
	global_load_dword v252, v249, s[98:99]
	s_add_u32 s98, s98, 0x2000
	s_addc_u32 s99, s99, 0
	global_load_dword v252, v249, s[98:99]
	s_add_u32 s98, s98, 0x2000
	s_addc_u32 s99, s99, 0
	global_load_dword v252, v249, s[98:99]
	s_add_u32 s98, s98, 0x2000
	s_addc_u32 s99, s99, 0
	global_load_dword v252, v249, s[98:99]
.Lsconv_pf_done:
	s_movk_i32 s13, 0x1680
	v_cmp_gt_i32_e32 vcc, s13, v6
	s_and_saveexec_b64 s[22:23], vcc
	s_cbranch_execz .LBB0_503
	v_lshl_add_u32 v7, v6, 4, 0
	s_mov_b64 s[42:43], 0
	s_movk_i32 s13, 0xf80
	v_mov_b32_e32 v5, 0
	s_movk_i32 s14, 0x147f
	v_mov_b32_e32 v4, v6
	s_branch .LBB0_501

	.amdhsa_kernel _Z6mk_fwdILi0ELi12EEv4Args
		.amdhsa_group_segment_fixed_size 0
		.amdhsa_private_segment_fixed_size 0
		.amdhsa_kernarg_size 504
		.amdhsa_user_sgpr_count 2
		.amdhsa_user_sgpr_dispatch_ptr 0
		.amdhsa_user_sgpr_queue_ptr 0
		.amdhsa_user_sgpr_kernarg_segment_ptr 1
		.amdhsa_user_sgpr_dispatch_id 0
		.amdhsa_user_sgpr_kernarg_preload_length 0
		.amdhsa_user_sgpr_kernarg_preload_offset 0
		.amdhsa_user_sgpr_private_segment_size 0
		.amdhsa_uses_dynamic_stack 0
		.amdhsa_enable_private_segment 0
		.amdhsa_system_sgpr_workgroup_id_x 1
		.amdhsa_system_sgpr_workgroup_id_y 0
		.amdhsa_system_sgpr_workgroup_id_z 0
		.amdhsa_system_sgpr_workgroup_info 0
		.amdhsa_system_vgpr_workitem_id 0
		.amdhsa_next_free_vgpr 253
		.amdhsa_next_free_sgpr 100
		.amdhsa_accum_offset 256
		.amdhsa_reserve_vcc 1
		.amdhsa_float_round_mode_32 0
		.amdhsa_float_round_mode_16_64 0
		.amdhsa_float_denorm_mode_32 3
		.amdhsa_float_denorm_mode_16_64 3
		.amdhsa_dx10_clamp 1
		.amdhsa_ieee_mode 1
		.amdhsa_fp16_overflow 0
		.amdhsa_tg_split 0
		.amdhsa_exception_fp_ieee_invalid_op 0
		.amdhsa_exception_fp_denorm_src 0
		.amdhsa_exception_fp_ieee_div_zero 0
		.amdhsa_exception_fp_ieee_overflow 0
		.amdhsa_exception_fp_ieee_underflow 0
		.amdhsa_exception_fp_ieee_inexact 0
		.amdhsa_exception_int_div_zero 0
	.end_amdhsa_kernel

amdhsa.kernels:
  - .agpr_count:     0
    .args:
      - .offset:         0
        .size:           248
        .value_kind:     by_value
      - .offset:         248
        .size:           4
        .value_kind:     hidden_block_count_x
      - .offset:         252
        .size:           4
        .value_kind:     hidden_block_count_y
      - .offset:         256
        .size:           4
        .value_kind:     hidden_block_count_z
      - .offset:         260
        .size:           2
        .value_kind:     hidden_group_size_x
      - .offset:         262
        .size:           2
        .value_kind:     hidden_group_size_y
      - .offset:         264
        .size:           2
        .value_kind:     hidden_group_size_z
      - .offset:         266
        .size:           2
        .value_kind:     hidden_remainder_x
      - .offset:         268
        .size:           2
        .value_kind:     hidden_remainder_y
      - .offset:         270
        .size:           2
        .value_kind:     hidden_remainder_z
      - .offset:         288
        .size:           8
        .value_kind:     hidden_global_offset_x
      - .offset:         296
        .size:           8
        .value_kind:     hidden_global_offset_y
      - .offset:         304
        .size:           8
        .value_kind:     hidden_global_offset_z
      - .offset:         312
        .size:           2
        .value_kind:     hidden_grid_dims
      - .offset:         368
        .size:           4
        .value_kind:     hidden_dynamic_lds_size
    .group_segment_fixed_size: 0
    .kernarg_segment_align: 8
    .kernarg_segment_size: 504
    .language:       OpenCL C
    .language_version:
      - 2
      - 0
    .max_flat_workgroup_size: 512
    .name:           _Z6mk_fwdILi0ELi12EEv4Args
    .private_segment_fixed_size: 0
    .sgpr_count:     106
    .sgpr_spill_count: 16
    .symbol:         _Z6mk_fwdILi0ELi12EEv4Args.kd
    .uniform_work_group_size: 1
    .uses_dynamic_stack: false
    .vgpr_count:     253
    .vgpr_spill_count: 0
    .wavefront_size: 64
